# FN: final-norm output stores use the nt (streaming) policy (output is written once, never re-read by the kernel), on top of C6+N3
# speedup vs baseline: 1.0074x; 1.0074x over previous
.LBB0_426:
	v_lshl_add_u64 v[30:31], v[18:19], 0, v[128:129]
	s_mov_b32 s0, 0x4279000
	v_add_co_u32_e64 v50, s[38:39], s0, v30
	v_add_co_u32_e32 v46, vcc, 0x4278000, v30
	s_nop 0
	v_addc_co_u32_e64 v51, s[38:39], 0, v31, s[38:39]
	global_load_dwordx4 v[4:7], v[50:51], off
	global_load_dwordx4 v[0:3], v[50:51], off offset:1024
	v_addc_co_u32_e32 v47, vcc, 0, v31, vcc
	global_load_dwordx4 v[30:33], v[50:51], off offset:2048
	global_load_dwordx4 v[34:37], v[46:47], off
	global_load_dwordx4 v[38:41], v[46:47], off offset:1024
	global_load_dwordx4 v[42:45], v[46:47], off offset:2048
	s_nop 0
	global_load_dwordx4 v[46:49], v[46:47], off offset:3072
	s_nop 0
	global_load_dwordx4 v[50:53], v[50:51], off offset:3072
	s_nop 0
	v_lshl_add_u64 v[58:59], v[20:21], 0, v[128:129]
	v_add_u32_e32 v22, s6, v22
	v_lshl_add_u64 v[18:19], v[18:19], 0, s[18:19]
	v_lshl_add_u64 v[20:21], v[20:21], 0, s[18:19]
	s_waitcnt vmcnt(0)
	v_mov_b32_e32 v70, v31
	v_mul_f32_e32 v29, v35, v35
	v_mul_f32_e32 v76, v39, v39
	v_mul_f32_e32 v77, v43, v43
	v_fmac_f32_e32 v29, v34, v34
	v_fmac_f32_e32 v76, v38, v38
	v_mov_b32_e32 v62, v5
	v_mov_b32_e32 v63, v1
	v_mul_f32_e32 v78, v47, v47
	v_fmac_f32_e32 v77, v42, v42
	v_fmac_f32_e32 v29, v36, v36
	v_fmac_f32_e32 v76, v40, v40
	v_mov_b32_e32 v60, v4
	v_mov_b32_e32 v61, v0
	v_pk_mul_f32 v[62:63], v[62:63], v[62:63]
	v_fmac_f32_e32 v78, v46, v46
	v_fmac_f32_e32 v77, v44, v44
	v_fmac_f32_e32 v29, v37, v37
	v_fmac_f32_e32 v76, v41, v41
	v_mov_b32_e32 v64, v6
	v_mov_b32_e32 v65, v2
	v_mov_b32_e32 v71, v51
	v_pk_fma_f32 v[60:61], v[60:61], v[60:61], v[62:63]
	v_fmac_f32_e32 v78, v48, v48
	v_fmac_f32_e32 v77, v45, v45
	v_add_f32_e32 v29, v29, v76
	v_mov_b32_e32 v66, v7
	v_mov_b32_e32 v67, v3
	v_mov_b32_e32 v68, v30
	v_mov_b32_e32 v69, v50
	v_pk_mul_f32 v[70:71], v[70:71], v[70:71]
	v_pk_fma_f32 v[60:61], v[64:65], v[64:65], v[60:61]
	v_fmac_f32_e32 v78, v49, v49
	v_add_f32_e32 v29, v29, v77
	v_mov_b32_e32 v72, v32
	v_mov_b32_e32 v73, v52
	v_pk_fma_f32 v[62:63], v[68:69], v[68:69], v[70:71]
	v_pk_fma_f32 v[60:61], v[66:67], v[66:67], v[60:61]
	v_add_f32_e32 v29, v29, v78
	v_mov_b32_e32 v74, v33
	v_mov_b32_e32 v75, v53
	v_pk_fma_f32 v[62:63], v[72:73], v[72:73], v[62:63]
	v_add_f32_e32 v29, v29, v60
	v_pk_fma_f32 v[62:63], v[74:75], v[74:75], v[62:63]
	v_add_f32_e32 v29, v29, v61
	v_add_f32_e32 v29, v29, v62
	v_add_f32_e32 v29, v29, v63
	ds_bpermute_b32 v60, v23, v29
	s_waitcnt lgkmcnt(0)
	v_add_f32_e32 v29, v29, v60
	ds_bpermute_b32 v60, v24, v29
	s_waitcnt lgkmcnt(0)
	v_add_f32_e32 v29, v29, v60
	ds_bpermute_b32 v60, v25, v29
	s_waitcnt lgkmcnt(0)
	v_add_f32_e32 v29, v29, v60
	ds_bpermute_b32 v60, v26, v29
	s_waitcnt lgkmcnt(0)
	v_add_f32_e32 v29, v29, v60
	ds_bpermute_b32 v60, v27, v29
	s_waitcnt lgkmcnt(0)
	v_add_f32_e32 v29, v29, v60
	ds_bpermute_b32 v60, v28, v29
	s_waitcnt lgkmcnt(0)
	v_add_f32_e32 v29, v29, v60
	v_fmamk_f32 v29, v29, 0x3a000000, v234
	v_mul_f32_e32 v60, 0x4b800000, v29
	v_cmp_gt_f32_e32 vcc, s25, v29
	s_nop 1
	v_cndmask_b32_e32 v29, v29, v60, vcc
	v_rsq_f32_e32 v29, v29
	s_nop 0
	v_mul_f32_e32 v60, 0x45800000, v29
	v_cndmask_b32_e32 v60, v29, v60, vcc
	v_pk_mul_f32 v[34:35], v[34:35], v[60:61] op_sel_hi:[1,0]
	v_pk_mul_f32 v[36:37], v[36:37], v[60:61] op_sel_hi:[1,0]
	v_pk_mul_f32 v[34:35], v[54:55], v[34:35]
	v_pk_mul_f32 v[36:37], v[56:57], v[36:37]
	global_store_dwordx4 v[58:59], v[34:37], off nt
	v_pk_mul_f32 v[40:41], v[40:41], v[60:61] op_sel_hi:[1,0]
	v_pk_mul_f32 v[38:39], v[38:39], v[60:61] op_sel_hi:[1,0]
	v_pk_mul_f32 v[6:7], v[6:7], v[60:61] op_sel_hi:[1,0]
	v_pk_mul_f32 v[4:5], v[4:5], v[60:61] op_sel_hi:[1,0]
	v_pk_mul_f32 v[2:3], v[2:3], v[60:61] op_sel_hi:[1,0]
	v_pk_mul_f32 v[0:1], v[0:1], v[60:61] op_sel_hi:[1,0]
	v_pk_mul_f32 v[34:35], v[80:81], v[38:39]
	v_pk_mul_f32 v[36:37], v[82:83], v[40:41]
	global_store_dwordx4 v[58:59], v[34:37], off offset:1024 nt
	s_nop 0
	v_pk_mul_f32 v[38:39], v[44:45], v[60:61] op_sel_hi:[1,0]
	v_pk_mul_f32 v[40:41], v[42:43], v[60:61] op_sel_hi:[1,0]
	v_pk_mul_f32 v[36:37], v[86:87], v[38:39]
	v_pk_mul_f32 v[34:35], v[84:85], v[40:41]
	global_store_dwordx4 v[58:59], v[34:37], off offset:2048 nt
	s_nop 0
	v_pk_mul_f32 v[38:39], v[48:49], v[60:61] op_sel_hi:[1,0]
	v_pk_mul_f32 v[40:41], v[46:47], v[60:61] op_sel_hi:[1,0]
	v_pk_mul_f32 v[36:37], v[90:91], v[38:39]
	v_pk_mul_f32 v[34:35], v[88:89], v[40:41]
	global_store_dwordx4 v[58:59], v[34:37], off offset:3072 nt
	v_add_co_u32_e32 v38, vcc, s85, v58
	v_pk_mul_f32 v[4:5], v[92:93], v[4:5]
	v_addc_co_u32_e32 v39, vcc, 0, v59, vcc
	v_pk_mul_f32 v[6:7], v[94:95], v[6:7]
	global_store_dwordx4 v[38:39], v[4:7], off nt
	v_cmp_lt_i32_e32 vcc, s7, v22
	s_or_b64 s[4:5], vcc, s[4:5]
	v_pk_mul_f32 v[0:1], v[96:97], v[0:1]
	v_pk_mul_f32 v[2:3], v[98:99], v[2:3]
	global_store_dwordx4 v[38:39], v[0:3], off offset:1024 nt
	s_nop 0
	v_pk_mul_f32 v[4:5], v[32:33], v[60:61] op_sel_hi:[1,0]
	v_pk_mul_f32 v[6:7], v[30:31], v[60:61] op_sel_hi:[1,0]
	v_pk_mul_f32 v[2:3], v[102:103], v[4:5]
	v_pk_mul_f32 v[0:1], v[100:101], v[6:7]
	global_store_dwordx4 v[38:39], v[0:3], off offset:2048 nt
	s_nop 0
	v_pk_mul_f32 v[4:5], v[52:53], v[60:61] op_sel_hi:[1,0]
	v_pk_mul_f32 v[6:7], v[50:51], v[60:61] op_sel_hi:[1,0]
	v_pk_mul_f32 v[2:3], v[106:107], v[4:5]
	v_pk_mul_f32 v[0:1], v[104:105], v[6:7]
	global_store_dwordx4 v[38:39], v[0:3], off offset:3072 nt
	s_andn2_b64 exec, exec, s[4:5]
	s_cbranch_execnz .LBB0_426
